# band step: rare O/l rescale block moved out of line as well
# baseline (speedup 1.0000x reference)
; DI void band_item(const Params& P, char* lds_blk, int layer, int bp) {
;     ...
;     for (int kt = kt0; kt < 4; ++kt) {
;         if (kt + 1 < 4) gload(kt + 1);
;         __syncthreads();
;         const int b = (kt - kt0) & 1;
;         const bool active = (64 * kt <= 128 + 32 * w + 31) && (64 * kt + 63 >= 128 + 32 * w - maxd);
;         if (active) {
.Lb3_noovr:
	s_add_i32 s0, s64, 63
	s_add_i32 s65, s65, 1
	v_cmp_le_u32_e32 vcc, s64, v126
	v_cmp_ge_u32_e64 s[0:1], s0, v128
	s_and_b32 s70, s65, 1
	s_and_b32 s70, s70, s101
	s_and_b64 s[72:73], vcc, s[0:1]
	s_waitcnt lgkmcnt(0)
	s_barrier
	s_and_saveexec_b64 s[0:1], s[72:73]
	s_cbranch_execz .LBB0_220
; #define LAS __attribute__((address_space(3)))
; #define MFMA(a, b, c) __builtin_amdgcn_mfma_f32_32x32x16_bf16((a), (b), (c), 0, 0, 0)
; template <int DVT>
; DI void attn_step(lptr sKw, int kpitch, lptr sV, int vpitch, const bf16x8 (&qf)[4], float& m, float& l, f32x16 (&O)[DVT],
;                   const LAS float* tb, bool far, float cfar, int lane) {
;     const int r = lane & 31, h = lane >> 5;
;     f32x16 p0, p1;
; #pragma unroll
;     for (int i = 0; i < 16; ++i) { p0[i] = 0.f; p1[i] = 0.f; }
;     bf16x8 kf[8];
; #pragma unroll
;     for (int s = 0; s < 4; ++s) {
;         kf[2 * s] = *(const LAS bf16x8*)(sKw + r * kpitch + (16 * s + 8 * h) * 2);
;         kf[2 * s + 1] = *(const LAS bf16x8*)(sKw + (32 + r) * kpitch + (16 * s + 8 * h) * 2);
;     }
;     __builtin_amdgcn_sched_barrier(0);
; #pragma unroll
;     for (int s = 0; s < 4; ++s) { p0 = MFMA(kf[2 * s], qf[s], p0); p1 = MFMA(kf[2 * s + 1], qf[s], p1); }
;     const int i16 = lane & 15, q = i16 >> 2, pp = i16 & 3, blk = (lane >> 4) & 1;
;     lptr vb = sV + (4 * h + q) * vpitch + (16 * blk + 4 * pp) * 2;
;     ...
;     ATTN_TAIL(DVT, VADDR_PAD)
	s_mul_i32 s71, s70, 0x4800
	v_add_u32_e32 v98, s71, v125
	v_add3_u32 v38, v98, v127, v112
	v_add3_u32 v39, v98, v129, v112
	ds_read_b128 v[34:37], v38
	ds_read_b128 v[50:53], v38 offset:32
	ds_read_b128 v[54:57], v39
	ds_read_b128 v[136:139], v39 offset:32
	ds_read_b128 v[58:61], v38 offset:64
	ds_read_b128 v[62:65], v38 offset:96
	ds_read_b128 v[140:143], v39 offset:64
	ds_read_b128 v[144:147], v39 offset:96
	s_waitcnt lgkmcnt(7)
	v_mfma_f32_32x32x16_bf16 v[34:49], v[34:37], v[66:69], 0
	s_waitcnt lgkmcnt(6)
	v_mfma_f32_32x32x16_bf16 v[34:49], v[50:53], v[70:73], v[34:49]
	v_add_u32_e32 v50, v98, v131
	v_add_u32_e32 v135, v50, v132
	ds_read_b64_tr_b16 v[102:103], v135 offset:9216
	ds_read_b64_tr_b16 v[104:105], v135 offset:10368
	ds_read_b64_tr_b16 v[100:101], v135 offset:10432
	ds_read_b64_tr_b16 v[98:99], v135 offset:9280
	s_waitcnt lgkmcnt(7)
	v_mfma_f32_32x32x16_bf16 v[34:49], v[58:61], v[74:77], v[34:49]
	s_waitcnt lgkmcnt(6)
	v_mfma_f32_32x32x16_bf16 v[34:49], v[62:65], v[78:81], v[34:49]
	v_mfma_f32_32x32x16_bf16 v[50:65], v[54:57], v[66:69], 0
	v_mfma_f32_32x32x16_bf16 v[50:65], v[136:139], v[70:73], v[50:65]
	ds_read2_b32 v[136:137], v134 offset0:58 offset1:59
	ds_read2_b32 v[138:139], v134 offset0:56 offset1:57
	ds_read2_b32 v[148:149], v134 offset0:50 offset1:51
	ds_read2_b32 v[150:151], v134 offset0:48 offset1:49
	ds_read2_b32 v[152:153], v134 offset0:26 offset1:27
	ds_read2_b32 v[154:155], v134 offset0:24 offset1:25
	ds_read2_b32 v[156:157], v134 offset0:18 offset1:19
	ds_read2_b32 v[158:159], v134 offset0:16 offset1:17
	s_waitcnt lgkmcnt(13)
	v_mfma_f32_32x32x16_bf16 v[50:65], v[140:143], v[74:77], v[50:65]
	ds_read2_b32 v[140:141], v134 offset0:42 offset1:43
	ds_read2_b32 v[142:143], v134 offset0:40 offset1:41
	ds_read2_b32 v[160:161], v134 offset0:34 offset1:35
	ds_read2_b32 v[162:163], v134 offset0:32 offset1:33
	ds_read2_b32 v[164:165], v134 offset0:10 offset1:11
	ds_read2_b32 v[166:167], v134 offset0:8 offset1:9
	ds_read2_b32 v[168:169], v134 offset0:2 offset1:3
	ds_read2_b32 v[170:171], v134 offset1:1
	s_waitcnt lgkmcnt(15)
	v_mfma_f32_32x32x16_bf16 v[50:65], v[144:147], v[78:81], v[50:65]
	s_waitcnt lgkmcnt(0)
	v_fmamk_f32 v137, v34, 0x3e38aa3b, v137
	v_fmamk_f32 v35, v35, 0x3e38aa3b, v136
	v_fmamk_f32 v36, v36, 0x3e38aa3b, v139
	v_fmamk_f32 v37, v37, 0x3e38aa3b, v138
	v_fmamk_f32 v38, v38, 0x3e38aa3b, v149
	v_fmamk_f32 v39, v39, 0x3e38aa3b, v148
	v_fmamk_f32 v40, v40, 0x3e38aa3b, v151
	v_fmamk_f32 v41, v41, 0x3e38aa3b, v150
	v_fmamk_f32 v42, v42, 0x3e38aa3b, v141
	v_fmamk_f32 v43, v43, 0x3e38aa3b, v140
	v_fmamk_f32 v44, v44, 0x3e38aa3b, v143
	v_fmamk_f32 v45, v45, 0x3e38aa3b, v142
	v_fmamk_f32 v46, v46, 0x3e38aa3b, v161
	v_fmamk_f32 v47, v47, 0x3e38aa3b, v160
	v_fmamk_f32 v48, v48, 0x3e38aa3b, v163
	v_fmamk_f32 v49, v49, 0x3e38aa3b, v162
	v_max3_f32 v34, v137, v35, v36
	v_max3_f32 v136, v37, v38, v39
	v_max3_f32 v34, v34, v40, v41
	v_max3_f32 v136, v136, v42, v43
	v_max3_f32 v34, v34, v44, v45
	v_max3_f32 v136, v136, v46, v47
	v_max3_f32 v34, v34, v48, v49
	v_fmamk_f32 v50, v50, 0x3e38aa3b, v153
	v_fmamk_f32 v51, v51, 0x3e38aa3b, v152
	v_fmamk_f32 v52, v52, 0x3e38aa3b, v155
	v_fmamk_f32 v53, v53, 0x3e38aa3b, v154
	v_fmamk_f32 v54, v54, 0x3e38aa3b, v157
	v_fmamk_f32 v55, v55, 0x3e38aa3b, v156
	v_fmamk_f32 v56, v56, 0x3e38aa3b, v159
	v_fmamk_f32 v57, v57, 0x3e38aa3b, v158
	v_fmamk_f32 v58, v58, 0x3e38aa3b, v165
	v_fmamk_f32 v59, v59, 0x3e38aa3b, v164
	v_fmamk_f32 v60, v60, 0x3e38aa3b, v167
	v_fmamk_f32 v61, v61, 0x3e38aa3b, v166
	v_fmamk_f32 v62, v62, 0x3e38aa3b, v169
	v_fmamk_f32 v63, v63, 0x3e38aa3b, v168
	v_fmamk_f32 v64, v64, 0x3e38aa3b, v171
	v_fmamk_f32 v65, v65, 0x3e38aa3b, v170
	v_max3_f32 v34, v34, v50, v51
	v_max3_f32 v136, v136, v52, v53
	v_max3_f32 v34, v34, v54, v55
	v_max3_f32 v136, v136, v56, v57
	v_max3_f32 v34, v34, v58, v59
	v_max3_f32 v136, v136, v60, v61
	v_max3_f32 v34, v34, v62, v63
	v_max3_f32 v136, v136, v64, v65
	s_nop 0
	v_max_f32_e32 v136, v136, v136
	v_max_f32_e32 v34, v34, v34
	v_max_f32_e32 v34, v34, v136
	v_mov_b32_e32 v136, v34
	s_nop 1
	v_permlane32_swap_b32_e32 v34, v136
	v_max_f32_e32 v136, v136, v136
	v_max_f32_e32 v34, v34, v34
	v_max_f32_e32 v34, v34, v136
	v_sub_f32_e32 v136, v34, v133
	v_cmp_lt_f32_e32 vcc, s45, v136
	v_max_f32_e32 v34, v133, v34
	s_nop 0
	v_cndmask_b32_e32 v34, v133, v34, vcc
	v_sub_f32 v136, v137, v34
	v_sub_f32 v50, v50, v34
	v_sub_f32 v51, v51, v34
	v_sub_f32 v36, v36, v34
	v_sub_f32 v52, v52, v34
	v_sub_f32 v53, v53, v34
	v_sub_f32 v54, v54, v34
	v_sub_f32 v39, v39, v34
	v_sub_f32 v55, v55, v34
	v_sub_f32 v40, v40, v34
	v_sub_f32 v56, v56, v34
	v_sub_f32 v57, v57, v34
	v_sub_f32 v58, v58, v34
	v_sub_f32 v43, v43, v34
	v_sub_f32 v44, v44, v34
	v_sub_f32 v47, v47, v34
	v_sub_f32 v48, v48, v34
	v_sub_f32 v137, v35, v34
	v_sub_f32 v138, v37, v34
	v_sub_f32 v139, v38, v34
	v_sub_f32 v140, v41, v34
	v_sub_f32 v141, v42, v34
	v_sub_f32 v142, v59, v34
	v_sub_f32 v143, v60, v34
	v_sub_f32 v144, v45, v34
	v_sub_f32 v145, v61, v34
	v_sub_f32 v146, v46, v34
	v_sub_f32 v147, v62, v34
	v_sub_f32 v148, v63, v34
	v_sub_f32 v149, v64, v34
	v_sub_f32 v150, v49, v34
	v_sub_f32 v151, v65, v34
	s_nop 0
	v_exp_f32_e32 v59, v136
	v_exp_f32_e32 v35, v50
	v_exp_f32_e32 v60, v137
	v_exp_f32_e32 v37, v51
	v_exp_f32_e32 v61, v36
	v_exp_f32_e32 v38, v52
	v_exp_f32_e32 v62, v138
	v_exp_f32_e32 v41, v53
	v_exp_f32_e32 v63, v139
	v_exp_f32_e32 v42, v54
	v_exp_f32_e32 v64, v39
	v_exp_f32_e32 v45, v55
	v_exp_f32_e32 v65, v40
	v_exp_f32_e32 v46, v56
	v_exp_f32_e32 v136, v140
	v_exp_f32_e32 v49, v57
	v_exp_f32_e32 v51, v141
	v_exp_f32_e32 v36, v58
	v_exp_f32_e32 v52, v43
	v_exp_f32_e32 v39, v142
	v_exp_f32_e32 v53, v44
	v_exp_f32_e32 v40, v143
	v_exp_f32_e32 v54, v144
	v_exp_f32_e32 v43, v145
	v_exp_f32_e32 v55, v146
	v_exp_f32_e32 v44, v147
	v_exp_f32_e32 v56, v47
	v_exp_f32_e32 v47, v148
	v_exp_f32_e32 v57, v48
	v_exp_f32_e32 v48, v149
	v_exp_f32_e32 v58, v150
	v_exp_f32_e32 v50, v151
	v_add_f32 v137, v59, v35
	v_add_f32 v138, v51, v36
	v_add_f32 v139, v52, v39
	v_add_f32 v140, v53, v40
	v_add_f32 v141, v54, v43
	v_add_f32 v142, v55, v44
	s_nop 1
	s_nop 0
	v_add_f32 v137, v137, v138
	v_add_f32 v138, v60, v37
	v_add_f32 v143, v56, v47
	v_add_f32 v144, v57, v48
	v_cmp_neq_f32_e32 vcc, v34, v133
	v_add_f32 v138, v138, v139
	v_add_f32 v139, v61, v38
	v_add_f32 v145, v58, v50
	s_nop 0
	v_add_f32 v139, v139, v140
	v_add_f32 v140, v62, v41
	v_add_f32 v137, v137, v138
	s_nop 0
	v_add_f32 v140, v140, v141
	v_add_f32 v141, v63, v42
	s_nop 0
	v_add_f32 v141, v141, v142
	v_add_f32 v142, v64, v45
	v_add_f32 v138, v139, v140
	s_nop 0
	v_add_f32 v142, v142, v143
	v_add_f32 v143, v65, v46
	v_add_f32 v137, v137, v138
	s_nop 0
	v_add_f32 v143, v143, v144
	v_add_f32 v144, v136, v49
	v_add_f32 v138, v141, v142
	s_nop 0
	v_add_f32 v144, v144, v145
	s_nop 0
	v_add_f32 v139, v143, v144
	s_nop 0
	v_add_f32 v138, v138, v139
	s_nop 0
	v_add_f32 v137, v137, v138
	s_cbranch_vccnz .Lb_rare_rs

.Lb_rare_rs:
	v_sub_f32_e32 v133, v133, v34
	v_exp_f32_e32 v138, v133
	s_nop 0
	v_mul_f32_e32 v124, v124, v138
	v_pk_mul_f32 v[32:33], v[32:33], v[138:139] op_sel_hi:[1,0]
	v_pk_mul_f32 v[30:31], v[30:31], v[138:139] op_sel_hi:[1,0]
	v_pk_mul_f32 v[28:29], v[28:29], v[138:139] op_sel_hi:[1,0]
	v_pk_mul_f32 v[26:27], v[26:27], v[138:139] op_sel_hi:[1,0]
	v_pk_mul_f32 v[24:25], v[24:25], v[138:139] op_sel_hi:[1,0]
	v_pk_mul_f32 v[22:23], v[22:23], v[138:139] op_sel_hi:[1,0]
	v_pk_mul_f32 v[20:21], v[20:21], v[138:139] op_sel_hi:[1,0]
	v_pk_mul_f32 v[18:19], v[18:19], v[138:139] op_sel_hi:[1,0]
	v_pk_mul_f32 v[16:17], v[16:17], v[138:139] op_sel_hi:[1,0]
	v_pk_mul_f32 v[14:15], v[14:15], v[138:139] op_sel_hi:[1,0]
	v_pk_mul_f32 v[12:13], v[12:13], v[138:139] op_sel_hi:[1,0]
	v_pk_mul_f32 v[10:11], v[10:11], v[138:139] op_sel_hi:[1,0]
	v_pk_mul_f32 v[8:9], v[8:9], v[138:139] op_sel_hi:[1,0]
	v_pk_mul_f32 v[6:7], v[6:7], v[138:139] op_sel_hi:[1,0]
	v_pk_mul_f32 v[4:5], v[4:5], v[138:139] op_sel_hi:[1,0]
	v_pk_mul_f32 v[2:3], v[2:3], v[138:139] op_sel_hi:[1,0]
	s_branch .LBB0_219
